# weight-conversion tiles 2576..2767 (layer-3 ffn_in) moved from the idle workgroups of ffn_in(2) to those of qkv(1)
# baseline (speedup 1.0000x reference)
.LBB0_505:
	s_and_b64 s[0:1], s[0:1], exec
	s_movk_i32 s0, 0x510
	s_cselect_b32 s28, s0, 0xa10
	s_movk_i32 s0, 0x6d0
	s_cselect_b32 s30, s0, 0xb80
	s_add_i32 s33, s33, s28
	v_mov_b32_e32 v32, v156
	s_cmp_ge_i32 s33, s30
	s_cbranch_scc1 .LBB0_664
	s_cmpk_gt_i32 s33, 0x15f
	s_mov_b64 s[24:25], -1
	s_cbranch_scc0 .LBB0_577
	s_cmpk_gt_u32 s33, 0x20f
	s_cbranch_scc0 .LBB0_574
	s_cmpk_gt_u32 s33, 0x28f
	s_cbranch_scc0 .LBB0_571
	s_cmpk_gt_u32 s33, 0x2cf
	s_cbranch_scc0 .LBB0_568
	s_cmpk_gt_u32 s33, 0x30f
	s_cbranch_scc0 .LBB0_565
	s_cmpk_gt_u32 s33, 0x36f
	s_cbranch_scc0 .LBB0_562
	s_cmpk_gt_u32 s33, 0x3af
	s_cbranch_scc0 .LBB0_559
	s_cmpk_gt_u32 s33, 0x50f
	s_cbranch_scc0 .LBB0_556
	s_cmpk_gt_u32 s33, 0x5bf
	s_cbranch_scc0 .LBB0_553
	s_cmpk_gt_u32 s33, 0x61f
	s_cbranch_scc0 .LBB0_550
	s_cmpk_gt_u32 s33, 0x6cf
	s_cbranch_scc0 .LBB0_547
	s_cmpk_gt_u32 s33, 0x70f
	s_cbranch_scc0 .LBB0_544
	s_cmpk_gt_u32 s33, 0x78f
	s_cbranch_scc0 .LBB0_541
	s_cmpk_gt_u32 s33, 0x7cf
	s_cbranch_scc0 .LBB0_538
	s_cmpk_gt_u32 s33, 0x8cf
	s_cbranch_scc0 .LBB0_535
	s_cmpk_gt_u32 s33, 0x92f
	s_cbranch_scc0 .LBB0_532
	s_cmpk_gt_u32 s33, 0x96f
	s_cbranch_scc0 .LBB0_529
	s_cmpk_gt_u32 s33, 0xacf
	s_mov_b64 s[4:5], -1
	s_cbranch_scc0 .LBB0_525
	s_load_dwordx2 s[0:1], s[72:73], 0xd8
	s_add_i32 s31, s33, 0xfffff530
	s_mov_b64 s[4:5], 0
	s_waitcnt lgkmcnt(0)
	s_add_u32 s0, s0, 0x2100000
	s_addc_u32 s1, s1, 0

.LBB0_798:
	s_and_b32 s0, 0xffff, s5
	s_cmp_lg_u32 s0, 0
	s_cselect_b64 s[0:1], -1, 0
	s_cmp_lg_u64 s[0:1], 0
	s_addc_u32 s0, s4, 0
	s_cmpk_eq_i32 s0, 0x100
	s_cbranch_scc0 .LBB0_955
	v_readlane_b32 s0, v255, 6
	s_cmp_eq_u32 s0, 3
	v_readlane_b32 s4, v254, 0
	s_cselect_b64 s[0:1], -1, 0
	s_cmpk_lt_i32 s4, 0xc0
	s_cselect_b64 s[4:5], -1, 0
	s_or_b64 s[0:1], s[0:1], s[4:5]
	s_and_b64 vcc, exec, s[0:1]
	s_cbranch_vccnz .LBB0_955
	v_readlane_b32 s0, v255, 6
	s_cmp_eq_u32 s0, 1
	s_movk_i32 s0, 0x8d0
	s_cselect_b32 s4, s0, 0xa10
	s_movk_i32 s0, 0x610
	s_cselect_b32 s5, s0, 0x810
	v_readlane_b32 s0, v255, 18
	v_readlane_b32 s1, v255, 19
	s_and_b64 s[0:1], s[0:1], exec
	s_cselect_b32 s0, 0x250, s5
	v_readlane_b32 s1, v254, 0
	s_cselect_b32 s40, 0x510, s4
	s_add_i32 s41, s1, s0
	v_mov_b32_e32 v32, v156
	s_cmp_ge_i32 s41, s40
	s_cbranch_scc1 .LBB0_955
	s_cmpk_gt_i32 s41, 0x15f
	s_mov_b64 s[24:25], -1
	s_cbranch_scc0 .LBB0_868
	s_cmpk_gt_u32 s41, 0x20f
	s_cbranch_scc0 .LBB0_865
	s_cmpk_gt_u32 s41, 0x28f
	s_cbranch_scc0 .LBB0_862
	s_cmpk_gt_u32 s41, 0x2cf
	s_cbranch_scc0 .LBB0_859
	s_cmpk_gt_u32 s41, 0x30f
	s_cbranch_scc0 .LBB0_856
	s_cmpk_gt_u32 s41, 0x36f
	s_cbranch_scc0 .LBB0_853
	s_cmpk_gt_u32 s41, 0x3af
	s_cbranch_scc0 .LBB0_850
	s_cmpk_gt_u32 s41, 0x50f
	s_cbranch_scc0 .LBB0_847
	s_cmpk_gt_u32 s41, 0x5bf
	s_cbranch_scc0 .LBB0_844
	s_cmpk_gt_u32 s41, 0x61f
	s_cbranch_scc0 .LBB0_841
	s_cmpk_gt_u32 s41, 0x6cf
	s_cbranch_scc0 .LBB0_838
	s_cmpk_gt_u32 s41, 0x70f
	s_cbranch_scc0 .LBB0_835
	s_cmpk_gt_u32 s41, 0x78f
	s_cbranch_scc0 .LBB0_832
	s_cmpk_gt_u32 s41, 0x7cf
	s_cbranch_scc0 .LBB0_829
	s_cmpk_gt_u32 s41, 0x8cf
	s_cbranch_scc0 .LBB0_826
	s_cmpk_gt_u32 s41, 0x92f
	s_cbranch_scc0 .LBB0_823
	s_cmpk_gt_u32 s41, 0x96f
	s_mov_b64 s[4:5], -1
	s_cbranch_scc0 .LBB0_819
	s_load_dwordx2 s[0:1], s[72:73], 0xd0
	s_add_i32 s33, s41, 0xfffff690
	s_mov_b64 s[4:5], 0
	s_waitcnt lgkmcnt(0)
	s_add_u32 s0, s0, 0x4200000
	s_addc_u32 s1, s1, 0
